# v50 + window-loop LDS-DMA with SGPR bases and constant lane offsets (drops 10 64-bit VALU adds and the per-step address SALU)
# baseline (speedup 1.0000x reference)
; DI float bf2f(bf16_t h) { return __uint_as_float(((unsigned)h) << 16); }
; DI float bflo(unsigned u) { return __uint_as_float(u << 16); }
; DI float bfhi(unsigned u) { return __uint_as_float(u & 0xffff0000u); }
; DI float sigmoidf(float x) { return __builtin_amdgcn_rcpf(1.f + __expf(-x)); }
; template <bool FIRST>
; DI void nsa_flush(const int quad, bf16_t* optr, const AttnSt& st, const float (&sc)[2]) {
; #pragma unroll
;   for (int h = 0; h < 2; ++h)
; #pragma unroll
;     for (int dt = 0; dt < 4; ++dt) {
;       uint2* q = (uint2*)(optr + h * 64 + dt * 16 + quad * 4);
;       f32x4 o = st.O[h][dt] * sc[h];
;       if (!FIRST) {
;         uint2 pv = *q;
;         o[0] += bflo(pv.x); o[1] += bfhi(pv.x); o[2] += bflo(pv.y); o[3] += bfhi(pv.y);
;       }
;       uint2 u;
;       u.x = pack2(o[0], o[1]);
;       u.y = pack2(o[2], o[3]);
;       *q = u;
;     }
; }
; template <bool FX>
; DI void nsa_tile(const Params& p, int b, int g, int tile, bf16_t* lds, const float CL) {
;     ...
;     {
;       float sc[2];
; #pragma unroll
;       for (int h = 0; h < 2; ++h) {
;         float l;
;         if (FX) {
;           l = st.L[h][0];
;         } else {
;           l = st.l[h];
;           l += shx(l, 16, lane);
;           l += shx(l, 32, lane);
;         }
;         sc[h] = (l > 0.f) ? sigmoidf(bf2f(ztok[C_GT + 1 * 8 + g * 4 + hp * 2 + h])) / l : 0.f;
;       }
;       nsa_flush<false>(quad, otok + hp * 128, st, sc);
;     }
.LBB0_679:
	s_or_b64 exec, exec, s[2:3]
	s_lshl_b32 s28, s7, 1
	v_lshl_add_u64 v[158:159], v[128:129], 0, s[28:29]
	global_load_dwordx2 v[220:221], v[158:159], off
	global_load_dwordx2 v[222:223], v[158:159], off offset:32
	global_load_dwordx2 v[224:225], v[158:159], off offset:64
	global_load_dwordx2 v[226:227], v[158:159], off offset:96
	global_load_dwordx2 v[228:229], v[158:159], off offset:128
	global_load_dwordx2 v[230:231], v[158:159], off offset:160
	global_load_dwordx2 v[232:233], v[158:159], off offset:192
	global_load_dwordx2 v[234:235], v[158:159], off offset:224
	v_mov_b32_e32 v49, v48
	v_mov_b32_e32 v178, v186
	s_mov_b32 s71, s26
	s_mov_b32 s28, s27
	s_waitcnt vmcnt(7)
	v_lshlrev_b32_e32 v54, 16, v220
	v_and_b32_e32 v55, 0xffff0000, v220
	v_lshlrev_b32_e32 v46, 16, v221
	v_and_b32_e32 v47, 0xffff0000, v221
	v_pk_fma_f32 v[50:51], v[50:51], v[56:57], v[54:55]
	v_pk_fma_f32 v[46:47], v[52:53], v[58:59], v[46:47]
	v_cvt_pk_bf16_f32 v50, v50, v51
	v_cvt_pk_bf16_f32 v51, v46, v47

; DI float bflo(unsigned u) { return __uint_as_float(u << 16); }
; DI float bfhi(unsigned u) { return __uint_as_float(u & 0xffff0000u); }
; template <bool FIRST>
; DI void nsa_flush(const int quad, bf16_t* optr, const AttnSt& st, const float (&sc)[2]) {
;     ...
;       uint2* q = (uint2*)(optr + h * 64 + dt * 16 + quad * 4);
;       f32x4 o = st.O[h][dt] * sc[h];
;       if (!FIRST) {
;         uint2 pv = *q;
;         o[0] += bflo(pv.x); o[1] += bfhi(pv.x); o[2] += bflo(pv.y); o[3] += bfhi(pv.y);
;       }
;       uint2 u;
;       u.x = pack2(o[0], o[1]);
;       u.y = pack2(o[2], o[3]);
;       *q = u;
	s_nop 0
	global_store_dwordx2 v[158:159], v[50:51], off
	s_waitcnt vmcnt(7)
	v_lshlrev_b32_e32 v50, 16, v222
	v_and_b32_e32 v51, 0xffff0000, v222
	v_lshlrev_b32_e32 v46, 16, v223
	v_and_b32_e32 v47, 0xffff0000, v223
	v_pk_fma_f32 v[42:43], v[42:43], v[56:57], v[50:51]
	v_pk_fma_f32 v[44:45], v[44:45], v[58:59], v[46:47]
	v_cvt_pk_bf16_f32 v42, v42, v43
	v_cvt_pk_bf16_f32 v43, v44, v45
	global_store_dwordx2 v[158:159], v[42:43], off offset:32

; DI float bflo(unsigned u) { return __uint_as_float(u << 16); }
; DI float bfhi(unsigned u) { return __uint_as_float(u & 0xffff0000u); }
; DI void st_reset(AttnSt& st) {
; #pragma unroll
;   for (int h = 0; h < 2; ++h) {
;     st.m[h] = -1e30f;
;     st.l[h] = 0.f;
;     st.L[h] = f32x4{0.f, 0.f, 0.f, 0.f};
; #pragma unroll
;     for (int dt = 0; dt < 4; ++dt) st.O[h][dt] = f32x4{0.f, 0.f, 0.f, 0.f};
;   }
; template <bool FIRST>
; DI void nsa_flush(const int quad, bf16_t* optr, const AttnSt& st, const float (&sc)[2]) {
;     ...
;       uint2* q = (uint2*)(optr + h * 64 + dt * 16 + quad * 4);
;       f32x4 o = st.O[h][dt] * sc[h];
;       if (!FIRST) {
;         uint2 pv = *q;
;         o[0] += bflo(pv.x); o[1] += bfhi(pv.x); o[2] += bflo(pv.y); o[3] += bfhi(pv.y);
;       }
;       uint2 u;
;       u.x = pack2(o[0], o[1]);
;       u.y = pack2(o[2], o[3]);
;       *q = u;
	v_mov_b32_e32 v46, 0
	v_mov_b32_e32 v47, v46
	v_mov_b32_e32 v54, v46
	v_mov_b32_e32 v55, v46
	v_mov_b32_e32 v50, v46
	v_mov_b32_e32 v51, v46
	v_mov_b32_e32 v52, v46
	v_mov_b32_e32 v53, v46
	s_waitcnt vmcnt(7)
	v_lshlrev_b32_e32 v44, 16, v224
	v_and_b32_e32 v45, 0xffff0000, v224
	v_lshlrev_b32_e32 v42, 16, v225
	v_and_b32_e32 v43, 0xffff0000, v225
	v_pk_fma_f32 v[38:39], v[38:39], v[56:57], v[44:45]
	v_pk_fma_f32 v[40:41], v[40:41], v[58:59], v[42:43]
	v_cvt_pk_bf16_f32 v38, v38, v39
	v_cvt_pk_bf16_f32 v39, v40, v41
	global_store_dwordx2 v[158:159], v[38:39], off offset:64

; DI float bflo(unsigned u) { return __uint_as_float(u << 16); }
; DI float bfhi(unsigned u) { return __uint_as_float(u & 0xffff0000u); }
; template <bool FIRST>
; DI void nsa_flush(const int quad, bf16_t* optr, const AttnSt& st, const float (&sc)[2]) {
;     ...
;       uint2* q = (uint2*)(optr + h * 64 + dt * 16 + quad * 4);
;       f32x4 o = st.O[h][dt] * sc[h];
;       if (!FIRST) {
;         uint2 pv = *q;
;         o[0] += bflo(pv.x); o[1] += bfhi(pv.x); o[2] += bflo(pv.y); o[3] += bfhi(pv.y);
;       }
;       uint2 u;
;       u.x = pack2(o[0], o[1]);
;       u.y = pack2(o[2], o[3]);
;       *q = u;
	v_mov_b32_e32 v42, v46
	v_mov_b32_e32 v43, v46
	v_mov_b32_e32 v44, v46
	v_mov_b32_e32 v45, v46
	s_waitcnt vmcnt(7)
	v_lshlrev_b32_e32 v40, 16, v226
	v_and_b32_e32 v41, 0xffff0000, v226
	v_lshlrev_b32_e32 v38, 16, v227
	v_and_b32_e32 v39, 0xffff0000, v227
	v_pk_fma_f32 v[34:35], v[34:35], v[56:57], v[40:41]
	v_pk_fma_f32 v[36:37], v[36:37], v[58:59], v[38:39]
	v_cvt_pk_bf16_f32 v34, v34, v35
	v_cvt_pk_bf16_f32 v35, v36, v37

; DI float bflo(unsigned u) { return __uint_as_float(u << 16); }
; DI float bfhi(unsigned u) { return __uint_as_float(u & 0xffff0000u); }
; template <bool FIRST>
; DI void nsa_flush(const int quad, bf16_t* optr, const AttnSt& st, const float (&sc)[2]) {
;     ...
;       uint2* q = (uint2*)(optr + h * 64 + dt * 16 + quad * 4);
;       f32x4 o = st.O[h][dt] * sc[h];
;       if (!FIRST) {
;         uint2 pv = *q;
;         o[0] += bflo(pv.x); o[1] += bfhi(pv.x); o[2] += bflo(pv.y); o[3] += bfhi(pv.y);
;       }
;       uint2 u;
;       u.x = pack2(o[0], o[1]);
;       u.y = pack2(o[2], o[3]);
;       *q = u;
	v_mov_b32_e32 v40, v46
	global_store_dwordx2 v[158:159], v[34:35], off offset:96
	v_mov_b32_e32 v34, v48
	v_mov_b32_e32 v35, v48
	v_mov_b32_e32 v41, v46
	v_mov_b32_e32 v56, v46
	v_mov_b32_e32 v57, v46
	s_waitcnt vmcnt(7)
	v_lshlrev_b32_e32 v38, 16, v228
	v_and_b32_e32 v39, 0xffff0000, v228
	v_lshlrev_b32_e32 v36, 16, v229
	v_and_b32_e32 v37, 0xffff0000, v229
	v_pk_fma_f32 v[30:31], v[30:31], v[34:35], v[38:39]
	v_pk_fma_f32 v[32:33], v[32:33], v[48:49], v[36:37]
	v_cvt_pk_bf16_f32 v30, v30, v31
	v_cvt_pk_bf16_f32 v31, v32, v33
	global_store_dwordx2 v[158:159], v[30:31], off offset:128

; DI float bflo(unsigned u) { return __uint_as_float(u << 16); }
; DI float bfhi(unsigned u) { return __uint_as_float(u & 0xffff0000u); }
; template <bool FIRST>
; DI void nsa_flush(const int quad, bf16_t* optr, const AttnSt& st, const float (&sc)[2]) {
;     ...
;       uint2* q = (uint2*)(optr + h * 64 + dt * 16 + quad * 4);
;       f32x4 o = st.O[h][dt] * sc[h];
;       if (!FIRST) {
;         uint2 pv = *q;
;         o[0] += bflo(pv.x); o[1] += bfhi(pv.x); o[2] += bflo(pv.y); o[3] += bfhi(pv.y);
;       }
;       uint2 u;
;       u.x = pack2(o[0], o[1]);
;       u.y = pack2(o[2], o[3]);
;       *q = u;
	v_mov_b32_e32 v38, v46
	v_mov_b32_e32 v39, v46
	v_mov_b32_e32 v36, v46
	v_mov_b32_e32 v37, v46
	s_waitcnt vmcnt(7)
	v_lshlrev_b32_e32 v32, 16, v230
	v_and_b32_e32 v33, 0xffff0000, v230
	v_lshlrev_b32_e32 v30, 16, v231
	v_and_b32_e32 v31, 0xffff0000, v231
	v_pk_fma_f32 v[26:27], v[26:27], v[34:35], v[32:33]
	v_pk_fma_f32 v[28:29], v[28:29], v[48:49], v[30:31]
	v_cvt_pk_bf16_f32 v26, v26, v27
	v_cvt_pk_bf16_f32 v27, v28, v29
	global_store_dwordx2 v[158:159], v[26:27], off offset:160

; DI float bflo(unsigned u) { return __uint_as_float(u << 16); }
; DI float bfhi(unsigned u) { return __uint_as_float(u & 0xffff0000u); }
; template <bool FIRST>
; DI void nsa_flush(const int quad, bf16_t* optr, const AttnSt& st, const float (&sc)[2]) {
;     ...
;       uint2* q = (uint2*)(optr + h * 64 + dt * 16 + quad * 4);
;       f32x4 o = st.O[h][dt] * sc[h];
;       if (!FIRST) {
;         uint2 pv = *q;
;         o[0] += bflo(pv.x); o[1] += bfhi(pv.x); o[2] += bflo(pv.y); o[3] += bfhi(pv.y);
;       }
;       uint2 u;
;       u.x = pack2(o[0], o[1]);
;       u.y = pack2(o[2], o[3]);
;       *q = u;
	v_mov_b32_e32 v30, v46
	v_mov_b32_e32 v31, v46
	v_mov_b32_e32 v32, v46
	v_mov_b32_e32 v33, v46
	s_waitcnt vmcnt(7)
	v_lshlrev_b32_e32 v28, 16, v232
	v_and_b32_e32 v29, 0xffff0000, v232
	v_lshlrev_b32_e32 v26, 16, v233
	v_and_b32_e32 v27, 0xffff0000, v233
	v_pk_fma_f32 v[22:23], v[22:23], v[34:35], v[28:29]
	v_pk_fma_f32 v[24:25], v[24:25], v[48:49], v[26:27]
	v_cvt_pk_bf16_f32 v22, v22, v23
	v_cvt_pk_bf16_f32 v23, v24, v25
	global_store_dwordx2 v[158:159], v[22:23], off offset:192

; template <bool FX>
; DI void nsa_tile(const Params& p, int b, int g, int tile, bf16_t* lds, const float CL) {
;     ...
;     st_reset(st);
;     {
;       const bf16_t* kb = zb + C_KW + g * 64;
;       const int s0 = (cur >= 8) ? cur - 8 : 0;
;       tile64_gload(tid, rk0, rk1, kb + (size_t)s0 * 64 * ZS, ZS);
;       tile64_gload(tid, rv0, rv1, vwT + s0 * 64, TS);
	v_mov_b32_e32 v26, v46
	v_mov_b32_e32 v27, v46
	v_mov_b32_e32 v28, v46
	v_mov_b32_e32 v29, v46
	s_waitcnt vmcnt(7)
	v_lshlrev_b32_e32 v24, 16, v234
	v_and_b32_e32 v25, 0xffff0000, v234
	v_lshlrev_b32_e32 v22, 16, v235
	v_and_b32_e32 v23, 0xffff0000, v235
	v_pk_fma_f32 v[18:19], v[18:19], v[34:35], v[24:25]
	v_pk_fma_f32 v[20:21], v[20:21], v[48:49], v[22:23]
	v_cvt_pk_bf16_f32 v18, v18, v19
	v_cvt_pk_bf16_f32 v19, v20, v21
	global_store_dwordx2 v[158:159], v[18:19], off offset:224
	s_and_b32 s88, s76, 0xffff3fff
	s_or_b32 s88, s88, 0x4000
	s_movk_i32 s84, 0x800
	s_mov_b32 s85, 0
	v_lshl_add_u64 v[58:59], v[146:147], 0, v[218:219]
	v_lshl_add_u64 v[60:61], v[148:149], 0, v[218:219]
	v_lshl_add_u64 v[62:63], v[150:151], 0, v[218:219]
	v_lshl_add_u64 v[64:65], v[152:153], 0, v[218:219]
	v_lshl_add_u64 v[58:59], v[58:59], 0, s[84:85]
	v_lshl_add_u64 v[60:61], v[60:61], 0, s[84:85]
	v_readfirstlane_b32 s80, v58
	v_readfirstlane_b32 s81, v59
	s_sub_u32 s80, s80, 0x40000000
	s_subb_u32 s81, s81, 0
	v_readfirstlane_b32 s82, v62
	v_readfirstlane_b32 s83, v63
	s_sub_u32 s82, s82, 0x40000000
	s_subb_u32 s83, s83, 0
	v_subrev_u32_e32 v58, s80, v58
	v_subrev_u32_e32 v60, s80, v60
	v_subrev_u32_e32 v62, s82, v62
	v_subrev_u32_e32 v64, s82, v64
	s_mov_b32 m0, s88
	s_add_u32 s86, s88, 0x1000
	global_load_lds_dwordx4 v58, s[80:81]
	s_mov_b32 m0, s86
	s_add_u32 s86, s88, 0x2000
	global_load_lds_dwordx4 v60, s[80:81]
	s_mov_b32 m0, s86
	s_add_u32 s86, s88, 0x3000
	global_load_lds_dwordx4 v62, s[82:83]
	s_mov_b32 m0, s86
	s_add_u32 s80, s80, 0xa8c00
	global_load_lds_dwordx4 v64, s[82:83]
	s_addc_u32 s81, s81, 0
	s_add_u32 s82, s82, 0x80
	s_addc_u32 s83, s83, 0
	s_xor_b32 s88, s88, 0xc000
	v_xor_b32_e32 v188, 0x4000, v188
	v_xor_b32_e32 v189, 0x4000, v189
	v_xor_b32_e32 v190, 0x4000, v190
	v_xor_b32_e32 v191, 0x4000, v191
	v_xor_b32_e32 v207, 0x4000, v207
	v_xor_b32_e32 v208, 0x4000, v208
	v_xor_b32_e32 v209, 0x4000, v209
	v_xor_b32_e32 v210, 0x4000, v210
	v_xor_b32_e32 v211, 0x4000, v211
	v_xor_b32_e32 v212, 0x4000, v212
	v_xor_b32_e32 v213, 0x4000, v213
	v_xor_b32_e32 v214, 0x4000, v214
	s_movk_i32 s89, 0x4000
	v_mov_b32_e32 v48, v46
	v_mov_b32_e32 v49, v46
	v_mov_b32_e32 v34, v46
	v_mov_b32_e32 v35, v46
	v_mov_b32_e32 v22, v46
	v_mov_b32_e32 v23, v46
	v_mov_b32_e32 v24, v46
	v_mov_b32_e32 v25, v46
	v_mov_b32_e32 v18, v46
	v_mov_b32_e32 v19, v46
	v_mov_b32_e32 v20, v46
	v_mov_b32_e32 v21, v46
	s_branch .LBB0_681

; template <bool FX>
; DI void nsa_tile(const Params& p, int b, int g, int tile, bf16_t* lds, const float CL) {
;     ...
;       for (int s = s0; s <= cur; ++s) {
;         __syncthreads();
;         tile64_sstore(tid, Ks, rk0, rk1);
;         tile64_sstore(tid, Vs, rv0, rv1);
;         __syncthreads();
;         if (s < cur) {
;           tile64_gload(tid, rk0, rk1, kb + (size_t)(s + 1) * 64 * ZS, ZS);
;           tile64_gload(tid, rv0, rv1, vwT + (s + 1) * 64, TS);
;         }
.LBB0_681:
	s_add_i32 s72, s71, -1
	s_cmp_ge_u32 s72, s25
	s_waitcnt vmcnt(0)
	s_barrier
	s_cbranch_scc1 .LBB0_683
	s_mov_b32 m0, s88
	s_add_u32 s86, s88, 0x1000
	global_load_lds_dwordx4 v58, s[80:81]
	s_mov_b32 m0, s86
	s_add_u32 s86, s88, 0x2000
	global_load_lds_dwordx4 v60, s[80:81]
	s_mov_b32 m0, s86
	s_add_u32 s86, s88, 0x3000
	global_load_lds_dwordx4 v62, s[82:83]
	s_mov_b32 m0, s86
	s_add_u32 s80, s80, 0xa8c00
	global_load_lds_dwordx4 v64, s[82:83]
	s_addc_u32 s81, s81, 0
	s_add_u32 s82, s82, 0x80
	s_addc_u32 s83, s83, 0
	s_xor_b32 s88, s88, 0xc000
